# static s_setprio 1 for waves 0-3 (other half) over the P4/P5 item loops
# speedup vs baseline: 1.0049x; 1.0049x over previous
.LBB0_611:
	v_readlane_b32 s0, v255, 14
	v_readlane_b32 s1, v255, 15
	s_and_b64 s[0:1], s[0:1], exec
	s_movk_i32 s0, 0x500
	s_cselect_b32 s74, s0, 0x400
	s_movk_i32 s0, 0x400
	s_cselect_b32 s64, 0x480, s0
	s_or_b32 s5, s64, 0x100
	s_add_i32 s22, s5, s74
	v_readfirstlane_b32 s0, v211
	s_nop 3
	s_lshr_b32 s0, s0, 8
	s_cmp_eq_u32 s0, 0
	s_cbranch_scc0 .Lprio4_done
	s_setprio 1

.LBB0_842:
	s_or_b64 exec, exec, s[0:1]
	s_lshl_b32 s25, s64, 1
	s_add_i32 s20, s25, s74
	v_readfirstlane_b32 s0, v211
	s_nop 3
	s_lshr_b32 s0, s0, 8
	s_cmp_eq_u32 s0, 0
	s_cbranch_scc0 .Lprio5_done
	s_setprio 1
